# G1 selection: all-pairs rank loop replaced by cross-lane bitonic top-16 network (DPP + v_med3_u32, 8 heads interleaved), same selected set
# speedup vs baseline: 1.0426x; 1.0106x over previous
.LBB0_975:
	s_or_b64 exec, exec, s[4:5]
	s_mov_b64 s[4:5], s[0:1]
	v_mov_b32_e32 v1, v176
	s_waitcnt lgkmcnt(0)
	s_barrier
	s_mov_b32 s46, 0x8400
	v_ashrrev_i32_e32 v0, 6, v1
	v_mul_lo_u32 v2, v0, s70
	v_add_u32_e32 v116, s2, v2
	s_lshl_b32 s33, s70, 3
	v_cmp_gt_i32_e32 vcc, s46, v116
	s_and_saveexec_b64 s[30:31], vcc
	s_cbranch_execz .LBB0_1038
	s_load_dwordx2 s[14:15], s[4:5], 0xf8
	v_ashrrev_i32_e32 v117, 31, v116
	v_and_b32_e32 v124, 63, v1
	v_lshlrev_b64 v[4:5], 10, v[116:117]
	v_mov_b32_e32 v3, 0
	s_waitcnt lgkmcnt(0)
	s_add_u32 s16, s14, 0xf347000
	s_addc_u32 s17, s15, 0
	v_lshrrev_b32_e32 v205, 4, v124
	v_lshrrev_b32_e32 v206, 5, v124
	v_lshrrev_b32_e32 v207, 0, v124
	v_xor_b32_e32 v196, v207, v205
	v_and_b32_e32 v196, 1, v196
	v_add_u32_e32 v196, -1, v196
	v_xor_b32_e32 v200, v207, v206
	v_and_b32_e32 v200, 1, v200
	v_add_u32_e32 v200, -1, v200
	v_lshrrev_b32_e32 v207, 1, v124
	v_xor_b32_e32 v197, v207, v205
	v_and_b32_e32 v197, 1, v197
	v_add_u32_e32 v197, -1, v197
	v_xor_b32_e32 v201, v207, v206
	v_and_b32_e32 v201, 1, v201
	v_add_u32_e32 v201, -1, v201
	v_lshrrev_b32_e32 v207, 2, v124
	v_xor_b32_e32 v198, v207, v205
	v_and_b32_e32 v198, 1, v198
	v_add_u32_e32 v198, -1, v198
	v_xor_b32_e32 v202, v207, v206
	v_and_b32_e32 v202, 1, v202
	v_add_u32_e32 v202, -1, v202
	v_lshrrev_b32_e32 v207, 3, v124
	v_xor_b32_e32 v199, v207, v205
	v_and_b32_e32 v199, 1, v199
	v_add_u32_e32 v199, -1, v199
	v_xor_b32_e32 v203, v207, v206
	v_and_b32_e32 v203, 1, v203
	v_add_u32_e32 v203, -1, v203
	v_mov_b32_e32 v204, 16
	s_getpc_b64 s[4:5]
	s_add_u32 s4, s4, _ZL7kStairJ@rel32@lo+4
	s_addc_u32 s5, s5, _ZL7kStairJ@rel32@hi+12
	v_lshlrev_b32_e32 v2, 4, v124
	s_getpc_b64 s[6:7]
	s_add_u32 s6, s6, _ZL7kStairI@rel32@lo+4
	s_addc_u32 s7, s7, _ZL7kStairI@rel32@hi+12
	v_lshl_add_u64 v[4:5], s[16:17], 0, v[4:5]
	global_load_ubyte v6, v124, s[4:5]
	global_load_ubyte v7, v124, s[6:7]
	v_lshl_add_u64 v[4:5], v[4:5], 0, v[2:3]
	global_load_dwordx4 v[112:115], v[4:5], off
	s_movk_i32 s4, 0x1600
	v_mul_lo_u32 v127, v0, s4
	s_add_u32 s36, s14, 0x2d27000
	v_and_b32_e32 v4, 31, v1
	v_and_b32_e32 v5, 8, v1
	v_and_b32_e32 v8, 4, v1
	v_and_b32_e32 v9, 2, v1
	v_and_b32_e32 v10, 1, v1
	v_lshlrev_b32_e32 v1, 1, v1
	v_add_u32_e32 v131, v127, v2
	s_addc_u32 s37, s15, 0
	v_lshlrev_b32_e32 v0, 2, v124
	v_and_b32_e32 v129, 60, v1
	v_and_or_b32 v1, v1, 64, v127
	v_mad_i32_i24 v133, v124, -12, v131
	v_lshl_add_u64 v[118:119], s[16:17], 0, v[2:3]
	v_lshlrev_b32_e32 v2, 3, v4
	s_add_u32 s38, s14, 0x2d37000
	s_mov_b64 s[18:19], 0x17747000
	v_add_u32_e32 v134, 0xc00, v1
	v_add_u32_e32 v135, v133, v0
	v_lshl_add_u64 v[0:1], s[14:15], 0, v[2:3]
	v_or_b32_e32 v136, 0x200, v2
	v_lshlrev_b32_e32 v2, 3, v124
	s_addc_u32 s39, s15, 0
	s_mov_b64 s[20:21], 0x11b47000
	v_mbcnt_lo_u32_b32 v11, -1, 0
	v_lshl_add_u64 v[120:121], v[0:1], 0, s[18:19]
	v_lshl_add_u64 v[0:1], s[14:15], 0, v[2:3]
	s_add_u32 s40, s14, 0xd27000
	s_mov_b64 s[34:35], 0
	s_mov_b32 s47, 0x83ff
	s_movk_i32 s48, 0xffc0
	s_movk_i32 s49, 0x3f80
	s_mov_b32 s50, 0xffff0000
	s_movk_i32 s51, 0x300
	s_mov_b32 s52, 0x378e98ab
	s_mov_b32 s53, 0x3b7cd369
	s_mov_b32 s54, 0xbcc618b2
	s_mov_b32 s55, 0x3dda74e4
	s_mov_b32 s56, 0x3f228afd
	s_mov_b32 s57, 0x3e03c728
	s_mov_b32 s58, 0xbfb8aa3b
	s_mov_b32 s59, 0x42ce8ed0
	s_mov_b32 s60, 0xc2b17218
	v_mov_b32_e32 v125, 0x3ba10414
	s_brev_b32 s61, -2
	s_mov_b32 s62, 0x44800000
	v_bfrev_b32_e32 v126, 1
	v_cmp_gt_u32_e64 s[4:5], 50, v124
	v_lshlrev_b32_e32 v128, 4, v4
	v_cmp_eq_u32_e64 s[6:7], 0, v5
	v_cmp_eq_u32_e64 s[8:9], 0, v8
	v_cmp_eq_u32_e64 s[10:11], 0, v9
	v_cmp_eq_u32_e64 s[12:13], 0, v10
	v_mbcnt_hi_u32_b32 v130, -1, v11
	v_add_u32_e32 v132, 0x400, v127
	v_lshl_add_u64 v[122:123], v[0:1], 0, s[20:21]
	s_addc_u32 s41, s15, 0
	v_mov_b32_e32 v139, 0xb9c68948
	v_mov_b32_e32 v140, 0x7f800000
	s_waitcnt vmcnt(2)
	v_lshl_add_u32 v138, v6, 2, v127
	s_waitcnt vmcnt(1)
	v_lshl_add_u32 v137, v7, 2, v127
	s_branch .LBB0_978

.LBB0_994:
	s_or_b64 exec, exec, s[16:17]
	v_ashrrev_i32_e32 v5, 31, v2
	v_or_b32_e32 v5, 0x80000000, v5
	v_bitop3_b32 v5, v5, s48, v2 bitop3:0x48
	v_bitop3_b32 v39, v5, 63, v124 bitop3:0x36
	ds_write_b32 v133, v39 offset:2816
	s_waitcnt lgkmcnt(0)
	s_and_b64 s[14:15], exec, vcc
	s_or_b64 s[34:35], s[14:15], s[34:35]
	v_mov_b32_e32 v40, v29
	v_mov_b32_e32 v41, v30
	v_mov_b32_e32 v42, v31
	v_mov_b32_e32 v43, v33
	v_mov_b32_e32 v44, v34
	v_mov_b32_e32 v45, v36
	v_mov_b32_e32 v46, v37
	v_mov_b32_e32 v47, v39
	v_mov_b32_e32 v48, 0
	v_mov_b32_e32 v49, 0
	v_mov_b32_e32 v50, 0
	v_mov_b32_e32 v51, 0
	v_mov_b32_e32 v52, 0
	v_mov_b32_e32 v53, 0
	v_mov_b32_e32 v54, 0
	v_mov_b32_e32 v55, 0
	v_mov_b32_dpp v48, v40 quad_perm:[1,0,3,2] row_mask:0xf bank_mask:0xf
	v_mov_b32_dpp v49, v41 quad_perm:[1,0,3,2] row_mask:0xf bank_mask:0xf
	v_mov_b32_dpp v50, v42 quad_perm:[1,0,3,2] row_mask:0xf bank_mask:0xf
	v_mov_b32_dpp v51, v43 quad_perm:[1,0,3,2] row_mask:0xf bank_mask:0xf
	v_mov_b32_dpp v52, v44 quad_perm:[1,0,3,2] row_mask:0xf bank_mask:0xf
	v_mov_b32_dpp v53, v45 quad_perm:[1,0,3,2] row_mask:0xf bank_mask:0xf
	v_mov_b32_dpp v54, v46 quad_perm:[1,0,3,2] row_mask:0xf bank_mask:0xf
	v_mov_b32_dpp v55, v47 quad_perm:[1,0,3,2] row_mask:0xf bank_mask:0xf
	v_med3_u32 v40, v40, v48, v196
	v_med3_u32 v41, v41, v49, v196
	v_med3_u32 v42, v42, v50, v196
	v_med3_u32 v43, v43, v51, v196
	v_med3_u32 v44, v44, v52, v196
	v_med3_u32 v45, v45, v53, v196
	v_med3_u32 v46, v46, v54, v196
	v_med3_u32 v47, v47, v55, v196
	v_mov_b32_dpp v48, v40 quad_perm:[3,2,1,0] row_mask:0xf bank_mask:0xf
	v_mov_b32_dpp v49, v41 quad_perm:[3,2,1,0] row_mask:0xf bank_mask:0xf
	v_mov_b32_dpp v50, v42 quad_perm:[3,2,1,0] row_mask:0xf bank_mask:0xf
	v_mov_b32_dpp v51, v43 quad_perm:[3,2,1,0] row_mask:0xf bank_mask:0xf
	v_mov_b32_dpp v52, v44 quad_perm:[3,2,1,0] row_mask:0xf bank_mask:0xf
	v_mov_b32_dpp v53, v45 quad_perm:[3,2,1,0] row_mask:0xf bank_mask:0xf
	v_mov_b32_dpp v54, v46 quad_perm:[3,2,1,0] row_mask:0xf bank_mask:0xf
	v_mov_b32_dpp v55, v47 quad_perm:[3,2,1,0] row_mask:0xf bank_mask:0xf
	v_med3_u32 v40, v40, v48, v197
	v_med3_u32 v41, v41, v49, v197
	v_med3_u32 v42, v42, v50, v197
	v_med3_u32 v43, v43, v51, v197
	v_med3_u32 v44, v44, v52, v197
	v_med3_u32 v45, v45, v53, v197
	v_med3_u32 v46, v46, v54, v197
	v_med3_u32 v47, v47, v55, v197
	v_mov_b32_dpp v48, v40 quad_perm:[1,0,3,2] row_mask:0xf bank_mask:0xf
	v_mov_b32_dpp v49, v41 quad_perm:[1,0,3,2] row_mask:0xf bank_mask:0xf
	v_mov_b32_dpp v50, v42 quad_perm:[1,0,3,2] row_mask:0xf bank_mask:0xf
	v_mov_b32_dpp v51, v43 quad_perm:[1,0,3,2] row_mask:0xf bank_mask:0xf
	v_mov_b32_dpp v52, v44 quad_perm:[1,0,3,2] row_mask:0xf bank_mask:0xf
	v_mov_b32_dpp v53, v45 quad_perm:[1,0,3,2] row_mask:0xf bank_mask:0xf
	v_mov_b32_dpp v54, v46 quad_perm:[1,0,3,2] row_mask:0xf bank_mask:0xf
	v_mov_b32_dpp v55, v47 quad_perm:[1,0,3,2] row_mask:0xf bank_mask:0xf
	v_med3_u32 v40, v40, v48, v196
	v_med3_u32 v41, v41, v49, v196
	v_med3_u32 v42, v42, v50, v196
	v_med3_u32 v43, v43, v51, v196
	v_med3_u32 v44, v44, v52, v196
	v_med3_u32 v45, v45, v53, v196
	v_med3_u32 v46, v46, v54, v196
	v_med3_u32 v47, v47, v55, v196
	v_mov_b32_dpp v48, v40 row_half_mirror row_mask:0xf bank_mask:0xf
	v_mov_b32_dpp v49, v41 row_half_mirror row_mask:0xf bank_mask:0xf
	v_mov_b32_dpp v50, v42 row_half_mirror row_mask:0xf bank_mask:0xf
	v_mov_b32_dpp v51, v43 row_half_mirror row_mask:0xf bank_mask:0xf
	v_mov_b32_dpp v52, v44 row_half_mirror row_mask:0xf bank_mask:0xf
	v_mov_b32_dpp v53, v45 row_half_mirror row_mask:0xf bank_mask:0xf
	v_mov_b32_dpp v54, v46 row_half_mirror row_mask:0xf bank_mask:0xf
	v_mov_b32_dpp v55, v47 row_half_mirror row_mask:0xf bank_mask:0xf
	v_med3_u32 v40, v40, v48, v198
	v_med3_u32 v41, v41, v49, v198
	v_med3_u32 v42, v42, v50, v198
	v_med3_u32 v43, v43, v51, v198
	v_med3_u32 v44, v44, v52, v198
	v_med3_u32 v45, v45, v53, v198
	v_med3_u32 v46, v46, v54, v198
	v_med3_u32 v47, v47, v55, v198
	v_mov_b32_dpp v48, v40 quad_perm:[2,3,0,1] row_mask:0xf bank_mask:0xf
	v_mov_b32_dpp v49, v41 quad_perm:[2,3,0,1] row_mask:0xf bank_mask:0xf
	v_mov_b32_dpp v50, v42 quad_perm:[2,3,0,1] row_mask:0xf bank_mask:0xf
	v_mov_b32_dpp v51, v43 quad_perm:[2,3,0,1] row_mask:0xf bank_mask:0xf
	v_mov_b32_dpp v52, v44 quad_perm:[2,3,0,1] row_mask:0xf bank_mask:0xf
	v_mov_b32_dpp v53, v45 quad_perm:[2,3,0,1] row_mask:0xf bank_mask:0xf
	v_mov_b32_dpp v54, v46 quad_perm:[2,3,0,1] row_mask:0xf bank_mask:0xf
	v_mov_b32_dpp v55, v47 quad_perm:[2,3,0,1] row_mask:0xf bank_mask:0xf
	v_med3_u32 v40, v40, v48, v197
	v_med3_u32 v41, v41, v49, v197
	v_med3_u32 v42, v42, v50, v197
	v_med3_u32 v43, v43, v51, v197
	v_med3_u32 v44, v44, v52, v197
	v_med3_u32 v45, v45, v53, v197
	v_med3_u32 v46, v46, v54, v197
	v_med3_u32 v47, v47, v55, v197
	v_mov_b32_dpp v48, v40 quad_perm:[1,0,3,2] row_mask:0xf bank_mask:0xf
	v_mov_b32_dpp v49, v41 quad_perm:[1,0,3,2] row_mask:0xf bank_mask:0xf
	v_mov_b32_dpp v50, v42 quad_perm:[1,0,3,2] row_mask:0xf bank_mask:0xf
	v_mov_b32_dpp v51, v43 quad_perm:[1,0,3,2] row_mask:0xf bank_mask:0xf
	v_mov_b32_dpp v52, v44 quad_perm:[1,0,3,2] row_mask:0xf bank_mask:0xf
	v_mov_b32_dpp v53, v45 quad_perm:[1,0,3,2] row_mask:0xf bank_mask:0xf
	v_mov_b32_dpp v54, v46 quad_perm:[1,0,3,2] row_mask:0xf bank_mask:0xf
	v_mov_b32_dpp v55, v47 quad_perm:[1,0,3,2] row_mask:0xf bank_mask:0xf
	v_med3_u32 v40, v40, v48, v196
	v_med3_u32 v41, v41, v49, v196
	v_med3_u32 v42, v42, v50, v196
	v_med3_u32 v43, v43, v51, v196
	v_med3_u32 v44, v44, v52, v196
	v_med3_u32 v45, v45, v53, v196
	v_med3_u32 v46, v46, v54, v196
	v_med3_u32 v47, v47, v55, v196
	v_mov_b32_dpp v48, v40 row_mirror row_mask:0xf bank_mask:0xf
	v_mov_b32_dpp v49, v41 row_mirror row_mask:0xf bank_mask:0xf
	v_mov_b32_dpp v50, v42 row_mirror row_mask:0xf bank_mask:0xf
	v_mov_b32_dpp v51, v43 row_mirror row_mask:0xf bank_mask:0xf
	v_mov_b32_dpp v52, v44 row_mirror row_mask:0xf bank_mask:0xf
	v_mov_b32_dpp v53, v45 row_mirror row_mask:0xf bank_mask:0xf
	v_mov_b32_dpp v54, v46 row_mirror row_mask:0xf bank_mask:0xf
	v_mov_b32_dpp v55, v47 row_mirror row_mask:0xf bank_mask:0xf
	v_med3_u32 v40, v40, v48, v199
	v_med3_u32 v41, v41, v49, v199
	v_med3_u32 v42, v42, v50, v199
	v_med3_u32 v43, v43, v51, v199
	v_med3_u32 v44, v44, v52, v199
	v_med3_u32 v45, v45, v53, v199
	v_med3_u32 v46, v46, v54, v199
	v_med3_u32 v47, v47, v55, v199
	v_mov_b32_dpp v48, v40 row_shl:4 row_mask:0xf bank_mask:0x5
	v_mov_b32_dpp v49, v41 row_shl:4 row_mask:0xf bank_mask:0x5
	v_mov_b32_dpp v50, v42 row_shl:4 row_mask:0xf bank_mask:0x5
	v_mov_b32_dpp v51, v43 row_shl:4 row_mask:0xf bank_mask:0x5
	v_mov_b32_dpp v52, v44 row_shl:4 row_mask:0xf bank_mask:0x5
	v_mov_b32_dpp v53, v45 row_shl:4 row_mask:0xf bank_mask:0x5
	v_mov_b32_dpp v54, v46 row_shl:4 row_mask:0xf bank_mask:0x5
	v_mov_b32_dpp v55, v47 row_shl:4 row_mask:0xf bank_mask:0x5
	v_mov_b32_dpp v48, v40 row_shr:4 row_mask:0xf bank_mask:0xa
	v_mov_b32_dpp v49, v41 row_shr:4 row_mask:0xf bank_mask:0xa
	v_mov_b32_dpp v50, v42 row_shr:4 row_mask:0xf bank_mask:0xa
	v_mov_b32_dpp v51, v43 row_shr:4 row_mask:0xf bank_mask:0xa
	v_mov_b32_dpp v52, v44 row_shr:4 row_mask:0xf bank_mask:0xa
	v_mov_b32_dpp v53, v45 row_shr:4 row_mask:0xf bank_mask:0xa
	v_mov_b32_dpp v54, v46 row_shr:4 row_mask:0xf bank_mask:0xa
	v_mov_b32_dpp v55, v47 row_shr:4 row_mask:0xf bank_mask:0xa
	v_med3_u32 v40, v40, v48, v198
	v_med3_u32 v41, v41, v49, v198
	v_med3_u32 v42, v42, v50, v198
	v_med3_u32 v43, v43, v51, v198
	v_med3_u32 v44, v44, v52, v198
	v_med3_u32 v45, v45, v53, v198
	v_med3_u32 v46, v46, v54, v198
	v_med3_u32 v47, v47, v55, v198
	v_mov_b32_dpp v48, v40 quad_perm:[2,3,0,1] row_mask:0xf bank_mask:0xf
	v_mov_b32_dpp v49, v41 quad_perm:[2,3,0,1] row_mask:0xf bank_mask:0xf
	v_mov_b32_dpp v50, v42 quad_perm:[2,3,0,1] row_mask:0xf bank_mask:0xf
	v_mov_b32_dpp v51, v43 quad_perm:[2,3,0,1] row_mask:0xf bank_mask:0xf
	v_mov_b32_dpp v52, v44 quad_perm:[2,3,0,1] row_mask:0xf bank_mask:0xf
	v_mov_b32_dpp v53, v45 quad_perm:[2,3,0,1] row_mask:0xf bank_mask:0xf
	v_mov_b32_dpp v54, v46 quad_perm:[2,3,0,1] row_mask:0xf bank_mask:0xf
	v_mov_b32_dpp v55, v47 quad_perm:[2,3,0,1] row_mask:0xf bank_mask:0xf
	v_med3_u32 v40, v40, v48, v197
	v_med3_u32 v41, v41, v49, v197
	v_med3_u32 v42, v42, v50, v197
	v_med3_u32 v43, v43, v51, v197
	v_med3_u32 v44, v44, v52, v197
	v_med3_u32 v45, v45, v53, v197
	v_med3_u32 v46, v46, v54, v197
	v_med3_u32 v47, v47, v55, v197
	v_mov_b32_dpp v48, v40 quad_perm:[1,0,3,2] row_mask:0xf bank_mask:0xf
	v_mov_b32_dpp v49, v41 quad_perm:[1,0,3,2] row_mask:0xf bank_mask:0xf
	v_mov_b32_dpp v50, v42 quad_perm:[1,0,3,2] row_mask:0xf bank_mask:0xf
	v_mov_b32_dpp v51, v43 quad_perm:[1,0,3,2] row_mask:0xf bank_mask:0xf
	v_mov_b32_dpp v52, v44 quad_perm:[1,0,3,2] row_mask:0xf bank_mask:0xf
	v_mov_b32_dpp v53, v45 quad_perm:[1,0,3,2] row_mask:0xf bank_mask:0xf
	v_mov_b32_dpp v54, v46 quad_perm:[1,0,3,2] row_mask:0xf bank_mask:0xf
	v_mov_b32_dpp v55, v47 quad_perm:[1,0,3,2] row_mask:0xf bank_mask:0xf
	v_med3_u32 v40, v40, v48, v196
	v_med3_u32 v41, v41, v49, v196
	v_med3_u32 v42, v42, v50, v196
	v_med3_u32 v43, v43, v51, v196
	v_med3_u32 v44, v44, v52, v196
	v_med3_u32 v45, v45, v53, v196
	v_med3_u32 v46, v46, v54, v196
	v_med3_u32 v47, v47, v55, v196
	v_mov_b32_e32 v56, v40
	v_mov_b32_e32 v57, v41
	v_mov_b32_e32 v58, v42
	v_mov_b32_e32 v59, v43
	v_mov_b32_e32 v60, v44
	v_mov_b32_e32 v61, v45
	v_mov_b32_e32 v62, v46
	v_mov_b32_e32 v63, v47
	v_permlane16_swap_b32_e32 v40, v56
	v_permlane16_swap_b32_e32 v41, v57
	v_permlane16_swap_b32_e32 v42, v58
	v_permlane16_swap_b32_e32 v43, v59
	v_permlane16_swap_b32_e32 v44, v60
	v_permlane16_swap_b32_e32 v45, v61
	v_permlane16_swap_b32_e32 v46, v62
	v_permlane16_swap_b32_e32 v47, v63
	v_max_u32_e32 v40, v40, v56
	v_max_u32_e32 v41, v41, v57
	v_max_u32_e32 v42, v42, v58
	v_max_u32_e32 v43, v43, v59
	v_max_u32_e32 v44, v44, v60
	v_max_u32_e32 v45, v45, v61
	v_max_u32_e32 v46, v46, v62
	v_max_u32_e32 v47, v47, v63
	v_mov_b32_dpp v48, v40 row_ror:8 row_mask:0xf bank_mask:0xf
	v_mov_b32_dpp v49, v41 row_ror:8 row_mask:0xf bank_mask:0xf
	v_mov_b32_dpp v50, v42 row_ror:8 row_mask:0xf bank_mask:0xf
	v_mov_b32_dpp v51, v43 row_ror:8 row_mask:0xf bank_mask:0xf
	v_mov_b32_dpp v52, v44 row_ror:8 row_mask:0xf bank_mask:0xf
	v_mov_b32_dpp v53, v45 row_ror:8 row_mask:0xf bank_mask:0xf
	v_mov_b32_dpp v54, v46 row_ror:8 row_mask:0xf bank_mask:0xf
	v_mov_b32_dpp v55, v47 row_ror:8 row_mask:0xf bank_mask:0xf
	v_med3_u32 v40, v40, v48, v203
	v_med3_u32 v41, v41, v49, v203
	v_med3_u32 v42, v42, v50, v203
	v_med3_u32 v43, v43, v51, v203
	v_med3_u32 v44, v44, v52, v203
	v_med3_u32 v45, v45, v53, v203
	v_med3_u32 v46, v46, v54, v203
	v_med3_u32 v47, v47, v55, v203
	v_mov_b32_dpp v48, v40 row_shl:4 row_mask:0xf bank_mask:0x5
	v_mov_b32_dpp v49, v41 row_shl:4 row_mask:0xf bank_mask:0x5
	v_mov_b32_dpp v50, v42 row_shl:4 row_mask:0xf bank_mask:0x5
	v_mov_b32_dpp v51, v43 row_shl:4 row_mask:0xf bank_mask:0x5
	v_mov_b32_dpp v52, v44 row_shl:4 row_mask:0xf bank_mask:0x5
	v_mov_b32_dpp v53, v45 row_shl:4 row_mask:0xf bank_mask:0x5
	v_mov_b32_dpp v54, v46 row_shl:4 row_mask:0xf bank_mask:0x5
	v_mov_b32_dpp v55, v47 row_shl:4 row_mask:0xf bank_mask:0x5
	v_mov_b32_dpp v48, v40 row_shr:4 row_mask:0xf bank_mask:0xa
	v_mov_b32_dpp v49, v41 row_shr:4 row_mask:0xf bank_mask:0xa
	v_mov_b32_dpp v50, v42 row_shr:4 row_mask:0xf bank_mask:0xa
	v_mov_b32_dpp v51, v43 row_shr:4 row_mask:0xf bank_mask:0xa
	v_mov_b32_dpp v52, v44 row_shr:4 row_mask:0xf bank_mask:0xa
	v_mov_b32_dpp v53, v45 row_shr:4 row_mask:0xf bank_mask:0xa
	v_mov_b32_dpp v54, v46 row_shr:4 row_mask:0xf bank_mask:0xa
	v_mov_b32_dpp v55, v47 row_shr:4 row_mask:0xf bank_mask:0xa
	v_med3_u32 v40, v40, v48, v202
	v_med3_u32 v41, v41, v49, v202
	v_med3_u32 v42, v42, v50, v202
	v_med3_u32 v43, v43, v51, v202
	v_med3_u32 v44, v44, v52, v202
	v_med3_u32 v45, v45, v53, v202
	v_med3_u32 v46, v46, v54, v202
	v_med3_u32 v47, v47, v55, v202
	v_mov_b32_dpp v48, v40 quad_perm:[2,3,0,1] row_mask:0xf bank_mask:0xf
	v_mov_b32_dpp v49, v41 quad_perm:[2,3,0,1] row_mask:0xf bank_mask:0xf
	v_mov_b32_dpp v50, v42 quad_perm:[2,3,0,1] row_mask:0xf bank_mask:0xf
	v_mov_b32_dpp v51, v43 quad_perm:[2,3,0,1] row_mask:0xf bank_mask:0xf
	v_mov_b32_dpp v52, v44 quad_perm:[2,3,0,1] row_mask:0xf bank_mask:0xf
	v_mov_b32_dpp v53, v45 quad_perm:[2,3,0,1] row_mask:0xf bank_mask:0xf
	v_mov_b32_dpp v54, v46 quad_perm:[2,3,0,1] row_mask:0xf bank_mask:0xf
	v_mov_b32_dpp v55, v47 quad_perm:[2,3,0,1] row_mask:0xf bank_mask:0xf
	v_med3_u32 v40, v40, v48, v201
	v_med3_u32 v41, v41, v49, v201
	v_med3_u32 v42, v42, v50, v201
	v_med3_u32 v43, v43, v51, v201
	v_med3_u32 v44, v44, v52, v201
	v_med3_u32 v45, v45, v53, v201
	v_med3_u32 v46, v46, v54, v201
	v_med3_u32 v47, v47, v55, v201
	v_mov_b32_dpp v48, v40 quad_perm:[1,0,3,2] row_mask:0xf bank_mask:0xf
	v_mov_b32_dpp v49, v41 quad_perm:[1,0,3,2] row_mask:0xf bank_mask:0xf
	v_mov_b32_dpp v50, v42 quad_perm:[1,0,3,2] row_mask:0xf bank_mask:0xf
	v_mov_b32_dpp v51, v43 quad_perm:[1,0,3,2] row_mask:0xf bank_mask:0xf
	v_mov_b32_dpp v52, v44 quad_perm:[1,0,3,2] row_mask:0xf bank_mask:0xf
	v_mov_b32_dpp v53, v45 quad_perm:[1,0,3,2] row_mask:0xf bank_mask:0xf
	v_mov_b32_dpp v54, v46 quad_perm:[1,0,3,2] row_mask:0xf bank_mask:0xf
	v_mov_b32_dpp v55, v47 quad_perm:[1,0,3,2] row_mask:0xf bank_mask:0xf
	v_med3_u32 v40, v40, v48, v200
	v_med3_u32 v41, v41, v49, v200
	v_med3_u32 v42, v42, v50, v200
	v_med3_u32 v43, v43, v51, v200
	v_med3_u32 v44, v44, v52, v200
	v_med3_u32 v45, v45, v53, v200
	v_med3_u32 v46, v46, v54, v200
	v_med3_u32 v47, v47, v55, v200
	v_mov_b32_e32 v56, v40
	v_mov_b32_e32 v57, v41
	v_mov_b32_e32 v58, v42
	v_mov_b32_e32 v59, v43
	v_mov_b32_e32 v60, v44
	v_mov_b32_e32 v61, v45
	v_mov_b32_e32 v62, v46
	v_mov_b32_e32 v63, v47
	v_permlane32_swap_b32_e32 v40, v56
	v_permlane32_swap_b32_e32 v41, v57
	v_permlane32_swap_b32_e32 v42, v58
	v_permlane32_swap_b32_e32 v43, v59
	v_permlane32_swap_b32_e32 v44, v60
	v_permlane32_swap_b32_e32 v45, v61
	v_permlane32_swap_b32_e32 v46, v62
	v_permlane32_swap_b32_e32 v47, v63
	v_max_u32_e32 v40, v40, v56
	v_max_u32_e32 v41, v41, v57
	v_max_u32_e32 v42, v42, v58
	v_max_u32_e32 v43, v43, v59
	v_max_u32_e32 v44, v44, v60
	v_max_u32_e32 v45, v45, v61
	v_max_u32_e32 v46, v46, v62
	v_max_u32_e32 v47, v47, v63
	v_min_u32_dpp v40, v40, v40 quad_perm:[1,0,3,2] row_mask:0xf bank_mask:0xf
	v_min_u32_dpp v41, v41, v41 quad_perm:[1,0,3,2] row_mask:0xf bank_mask:0xf
	v_min_u32_dpp v42, v42, v42 quad_perm:[1,0,3,2] row_mask:0xf bank_mask:0xf
	v_min_u32_dpp v43, v43, v43 quad_perm:[1,0,3,2] row_mask:0xf bank_mask:0xf
	v_min_u32_dpp v44, v44, v44 quad_perm:[1,0,3,2] row_mask:0xf bank_mask:0xf
	v_min_u32_dpp v45, v45, v45 quad_perm:[1,0,3,2] row_mask:0xf bank_mask:0xf
	v_min_u32_dpp v46, v46, v46 quad_perm:[1,0,3,2] row_mask:0xf bank_mask:0xf
	v_min_u32_dpp v47, v47, v47 quad_perm:[1,0,3,2] row_mask:0xf bank_mask:0xf
	v_min_u32_dpp v40, v40, v40 quad_perm:[2,3,0,1] row_mask:0xf bank_mask:0xf
	v_min_u32_dpp v41, v41, v41 quad_perm:[2,3,0,1] row_mask:0xf bank_mask:0xf
	v_min_u32_dpp v42, v42, v42 quad_perm:[2,3,0,1] row_mask:0xf bank_mask:0xf
	v_min_u32_dpp v43, v43, v43 quad_perm:[2,3,0,1] row_mask:0xf bank_mask:0xf
	v_min_u32_dpp v44, v44, v44 quad_perm:[2,3,0,1] row_mask:0xf bank_mask:0xf
	v_min_u32_dpp v45, v45, v45 quad_perm:[2,3,0,1] row_mask:0xf bank_mask:0xf
	v_min_u32_dpp v46, v46, v46 quad_perm:[2,3,0,1] row_mask:0xf bank_mask:0xf
	v_min_u32_dpp v47, v47, v47 quad_perm:[2,3,0,1] row_mask:0xf bank_mask:0xf
	v_min_u32_dpp v40, v40, v40 row_half_mirror row_mask:0xf bank_mask:0xf
	v_min_u32_dpp v41, v41, v41 row_half_mirror row_mask:0xf bank_mask:0xf
	v_min_u32_dpp v42, v42, v42 row_half_mirror row_mask:0xf bank_mask:0xf
	v_min_u32_dpp v43, v43, v43 row_half_mirror row_mask:0xf bank_mask:0xf
	v_min_u32_dpp v44, v44, v44 row_half_mirror row_mask:0xf bank_mask:0xf
	v_min_u32_dpp v45, v45, v45 row_half_mirror row_mask:0xf bank_mask:0xf
	v_min_u32_dpp v46, v46, v46 row_half_mirror row_mask:0xf bank_mask:0xf
	v_min_u32_dpp v47, v47, v47 row_half_mirror row_mask:0xf bank_mask:0xf
	v_min_u32_dpp v40, v40, v40 row_mirror row_mask:0xf bank_mask:0xf
	v_min_u32_dpp v41, v41, v41 row_mirror row_mask:0xf bank_mask:0xf
	v_min_u32_dpp v42, v42, v42 row_mirror row_mask:0xf bank_mask:0xf
	v_min_u32_dpp v43, v43, v43 row_mirror row_mask:0xf bank_mask:0xf
	v_min_u32_dpp v44, v44, v44 row_mirror row_mask:0xf bank_mask:0xf
	v_min_u32_dpp v45, v45, v45 row_mirror row_mask:0xf bank_mask:0xf
	v_min_u32_dpp v46, v46, v46 row_mirror row_mask:0xf bank_mask:0xf
	v_min_u32_dpp v47, v47, v47 row_mirror row_mask:0xf bank_mask:0xf
	v_readlane_b32 s80, v40, 0
	v_readlane_b32 s81, v41, 0
	v_readlane_b32 s82, v42, 0
	v_readlane_b32 s83, v43, 0
	v_readlane_b32 s84, v44, 0
	v_readlane_b32 s85, v45, 0
	v_readlane_b32 s86, v46, 0
	v_readlane_b32 s87, v47, 0
	v_cmp_gt_u32_e64 s[66:67], s80, v29
	v_cmp_gt_u32_e64 s[68:69], s81, v30
	v_cmp_gt_u32_e64 s[72:73], s82, v31
	v_cmp_gt_u32_e64 s[74:75], s83, v33
	v_cmp_gt_u32_e64 s[76:77], s84, v34
	v_cmp_gt_u32_e64 s[78:79], s85, v36
	v_cmp_gt_u32_e64 s[88:89], s86, v37
	v_cmp_gt_u32_e64 s[90:91], s87, v39
	v_cndmask_b32_e64 v38, 0, v204, s[66:67]
	v_cndmask_b32_e64 v35, 0, v204, s[68:69]
	v_cndmask_b32_e64 v32, 0, v204, s[72:73]
	v_cndmask_b32_e64 v28, 0, v204, s[74:75]
	v_cndmask_b32_e64 v24, 0, v204, s[76:77]
	v_cndmask_b32_e64 v19, 0, v204, s[78:79]
	v_cndmask_b32_e64 v12, 0, v204, s[88:89]
	v_cndmask_b32_e64 v5, 0, v204, s[90:91]
	s_mov_b32 s77, 0
	s_movk_i32 s78, 0x7f
	v_readfirstlane_b32 s14, v27
	v_cmp_gt_i32_e32 vcc, 16, v38
	v_mov_b32_e32 v143, 0
	v_subrev_f32_e32 v27, s14, v27
	v_mul_f32_e32 v27, 0x3fb8aa3b, v27
	v_exp_f32_e32 v27, v27
	s_and_b64 s[14:15], s[4:5], vcc
	v_lshl_add_u32 v142, v38, 2, v127
	v_xor_b32_e32 v184, v25, v26
	v_and_b32_e32 v184, 64, v184
	v_cmp_eq_u32_e32 vcc, 0, v184
	s_and_b64 s[72:73], vcc, s[14:15]
	s_andn2_b64 s[74:75], s[14:15], vcc
	v_mbcnt_lo_u32_b32 v184, s72, 0
	v_mbcnt_hi_u32_b32 v184, s73, v184
	v_mbcnt_lo_u32_b32 v185, s74, 0
	v_mbcnt_hi_u32_b32 v185, s75, v185
	v_add_u32_e32 v184, s77, v184
	v_sub_u32_e32 v185, s78, v185
	v_cndmask_b32_e32 v184, v185, v184, vcc
	v_lshl_add_u32 v142, v184, 2, v127
	s_bcnt1_i32_b64 s76, s[72:73]
	s_add_u32 s77, s77, s76
	s_bcnt1_i32_b64 s76, s[74:75]
	s_sub_u32 s78, s78, s76
	v_mov_b32_e32 v144, 0
	v_cndmask_b32_e64 v29, 0, v27, s[14:15]
	v_mov_b32_e32 v30, v29
	s_nop 1
	v_permlane32_swap_b32_e32 v29, v30
	v_add_f32_e32 v29, v29, v30
	v_mov_b32_e32 v30, v29
	s_nop 1
	v_permlane16_swap_b32_e32 v29, v30
	v_add_f32_e32 v29, v29, v30
	v_mov_b32_e32 v145, 0
	s_nop 0
	v_add_f32_dpp v29, v29, v29 row_ror:8 row_mask:0xf bank_mask:0xf bound_ctrl:1
	s_nop 1
	v_add_f32_dpp v29, v29, v29 row_ror:4 row_mask:0xf bank_mask:0xf bound_ctrl:1
	s_nop 1
	v_add_f32_dpp v29, v29, v29 quad_perm:[2,3,0,1] row_mask:0xf bank_mask:0xf bound_ctrl:1
	s_nop 1
	v_mov_b32_dpp v30, v29 quad_perm:[1,0,3,2] row_mask:0xf bank_mask:0xf bound_ctrl:1
	s_and_saveexec_b64 s[16:17], s[14:15]
	s_cbranch_execz .LBB0_998
	v_lshlrev_b32_e32 v25, 7, v25
	v_and_b32_e32 v26, 0x7f, v26
	v_and_or_b32 v25, v25, s49, v26
	v_lshlrev_b32_e32 v26, 2, v25
	global_load_dword v145, v26, s[36:37]
	global_load_dword v144, v26, s[38:39]
	v_add_f32_e32 v26, v29, v30
	v_div_scale_f32 v29, s[18:19], v26, v26, v27
	v_rcp_f32_e32 v30, v29
	s_nop 0
	v_fma_f32 v31, -v29, v30, 1.0
	v_fmac_f32_e32 v30, v31, v30
	v_div_scale_f32 v31, vcc, v27, v26, v27
	v_mul_f32_e32 v33, v31, v30
	v_fma_f32 v34, -v29, v33, v31
	v_fmac_f32_e32 v33, v34, v30
	v_fma_f32 v29, -v29, v33, v31
	v_div_fmas_f32 v29, v29, v30, v33
	v_div_fixup_f32 v26, v29, v26, v27
	ds_write2st64_b32 v142, v25, v26 offset0:12 offset1:14
